# Y (down/out GEMM) epilogue regenerated: bf16 convert + lane-transposed coalesced stores via ds_bpermute, double-buffered
# speedup vs baseline: 1.0076x; 1.0076x over previous
; __device__ __forceinline__ unsigned pk2(float lo, float hi) { return pg8::cvt_pk_bf16(lo, hi); }
; __device__ __forceinline__ float gelu_tanh(float x) { const float u = 1.5957691216057308f * (x + 0.044715f * x * x * x); return x * sigmoidf_(u); }
;     __device__ __forceinline__ void operator()(const f32x4 (&acc)[2][2][4][2], const pg8::Unit& u, int wr, int wc, int fr, int fq) const {
;     ...
;         for (int ai = 0; ai < 2; ++ai)
; #pragma unroll
;             for (int m = 0; m < 4; ++m) {
;                 const int row = row0 + ai * 128 + m * 16;
;                 bf16_t* rowp = O + (size_t)row * ldc + col0;
;                 float s = 0.f, ss = 0.f;
; #pragma unroll
;                 for (int bj = 0; bj < 2; ++bj) {
;                     f32x4 v0 = acc[ai][bj][m][0] + bv[bj][0], v1 = acc[ai][bj][m][1] + bv[bj][1];
;                     if (do_gelu) {
; #pragma unroll
;                         for (int e = 0; e < 4; ++e) { v0[e] = gelu_tanh(v0[e]); v1[e] = gelu_tanh(v1[e]); }
;                     }
; #pragma unroll
;                     for (int e = 0; e < 4; ++e) { s += v0[e] + v1[e]; ss += v0[e] * v0[e] + v1[e] * v1[e]; }
;                     u32x4 w; w.x = pk2(v0[0], v0[1]); w.y = pk2(v0[2], v0[3]); w.z = pk2(v1[0], v1[1]); w.w = pk2(v1[2], v1[3]);
;                     *(u32x4*)(rowp + bj * 128) = w;
;                 }
.LBB0_397:
	v_and_b32_e32 v204, 63, v163
	v_and_b32_e32 v205, 3, v204
	v_lshrrev_b32_e32 v206, 2, v204
	v_lshl_add_u32 v204, v205, 4, v206
	v_lshlrev_b32_e32 v204, 2, v204
	v_and_b32_e32 v207, 64, v146
	v_add_u32_e32 v207, v207, v206
	v_lshl_add_u32 v207, s84, 8, v207
	v_and_b32_e32 v206, 0x60, v148
	v_lshl_add_u32 v206, v205, 3, v206
	v_lshl_or_b32 v206, s83, 8, v206
	v_lshlrev_b32_e32 v206, 1, v206
	v_lshl_add_u32 v207, v207, 11, v206
	v_cvt_pk_bf16_f32 v188, v124, v125
	v_cvt_pk_bf16_f32 v189, v126, v127
	v_cvt_pk_bf16_f32 v190, v120, v121
	v_cvt_pk_bf16_f32 v191, v122, v123
	v_cvt_pk_bf16_f32 v192, v116, v117
	v_cvt_pk_bf16_f32 v193, v118, v119
	v_cvt_pk_bf16_f32 v194, v112, v113
	v_cvt_pk_bf16_f32 v195, v114, v115
	ds_bpermute_b32 v196, v204, v188
	ds_bpermute_b32 v197, v204, v189
	ds_bpermute_b32 v198, v204, v190
	ds_bpermute_b32 v199, v204, v191
	ds_bpermute_b32 v200, v204, v192
	ds_bpermute_b32 v201, v204, v193
	ds_bpermute_b32 v202, v204, v194
	ds_bpermute_b32 v203, v204, v195
	v_cvt_pk_bf16_f32 v208, v108, v109
	v_cvt_pk_bf16_f32 v209, v110, v111
	v_cvt_pk_bf16_f32 v210, v104, v105
	v_cvt_pk_bf16_f32 v211, v106, v107
	v_cvt_pk_bf16_f32 v212, v100, v101
	v_cvt_pk_bf16_f32 v213, v102, v103
	v_cvt_pk_bf16_f32 v214, v96, v97
	v_cvt_pk_bf16_f32 v215, v98, v99
	ds_bpermute_b32 v216, v204, v208
	ds_bpermute_b32 v217, v204, v209
	ds_bpermute_b32 v218, v204, v210
	ds_bpermute_b32 v219, v204, v211
	ds_bpermute_b32 v220, v204, v212
	ds_bpermute_b32 v221, v204, v213
	ds_bpermute_b32 v222, v204, v214
	ds_bpermute_b32 v223, v204, v215
	s_waitcnt lgkmcnt(8)
	global_store_dwordx4 v207, v[196:199], s[64:65]
	global_store_dwordx4 v207, v[200:203], s[64:65] offset:256
	v_add_u32_e32 v207, 0x8000, v207
	v_cvt_pk_bf16_f32 v188, v92, v93
	v_cvt_pk_bf16_f32 v189, v94, v95
	v_cvt_pk_bf16_f32 v190, v88, v89
	v_cvt_pk_bf16_f32 v191, v90, v91
	v_cvt_pk_bf16_f32 v192, v84, v85
	v_cvt_pk_bf16_f32 v193, v86, v87
	v_cvt_pk_bf16_f32 v194, v80, v81
	v_cvt_pk_bf16_f32 v195, v82, v83
	ds_bpermute_b32 v196, v204, v188
	ds_bpermute_b32 v197, v204, v189
	ds_bpermute_b32 v198, v204, v190
	ds_bpermute_b32 v199, v204, v191
	ds_bpermute_b32 v200, v204, v192
	ds_bpermute_b32 v201, v204, v193
	ds_bpermute_b32 v202, v204, v194
	ds_bpermute_b32 v203, v204, v195
	s_waitcnt lgkmcnt(8)
	global_store_dwordx4 v207, v[216:219], s[64:65]
	global_store_dwordx4 v207, v[220:223], s[64:65] offset:256
	v_add_u32_e32 v207, 0x8000, v207
	v_cvt_pk_bf16_f32 v208, v76, v77
	v_cvt_pk_bf16_f32 v209, v78, v79
	v_cvt_pk_bf16_f32 v210, v72, v73
	v_cvt_pk_bf16_f32 v211, v74, v75
	v_cvt_pk_bf16_f32 v212, v68, v69
	v_cvt_pk_bf16_f32 v213, v70, v71
	v_cvt_pk_bf16_f32 v214, v64, v65
	v_cvt_pk_bf16_f32 v215, v66, v67
	ds_bpermute_b32 v216, v204, v208
	ds_bpermute_b32 v217, v204, v209
	ds_bpermute_b32 v218, v204, v210
	ds_bpermute_b32 v219, v204, v211
	ds_bpermute_b32 v220, v204, v212
	ds_bpermute_b32 v221, v204, v213
	ds_bpermute_b32 v222, v204, v214
	ds_bpermute_b32 v223, v204, v215
	s_waitcnt lgkmcnt(8)
	global_store_dwordx4 v207, v[196:199], s[64:65]
	global_store_dwordx4 v207, v[200:203], s[64:65] offset:256
	v_add_u32_e32 v207, 0x8000, v207
	v_cvt_pk_bf16_f32 v188, v60, v61
	v_cvt_pk_bf16_f32 v189, v62, v63
	v_cvt_pk_bf16_f32 v190, v56, v57
	v_cvt_pk_bf16_f32 v191, v58, v59
	v_cvt_pk_bf16_f32 v192, v52, v53
	v_cvt_pk_bf16_f32 v193, v54, v55
	v_cvt_pk_bf16_f32 v194, v48, v49
	v_cvt_pk_bf16_f32 v195, v50, v51
	ds_bpermute_b32 v196, v204, v188
	ds_bpermute_b32 v197, v204, v189
	ds_bpermute_b32 v198, v204, v190
	ds_bpermute_b32 v199, v204, v191
	ds_bpermute_b32 v200, v204, v192
	ds_bpermute_b32 v201, v204, v193
	ds_bpermute_b32 v202, v204, v194
	ds_bpermute_b32 v203, v204, v195
	s_waitcnt lgkmcnt(8)
	global_store_dwordx4 v207, v[216:219], s[64:65]
	global_store_dwordx4 v207, v[220:223], s[64:65] offset:256
	v_add_u32_e32 v207, 0x28000, v207
	v_cvt_pk_bf16_f32 v208, v44, v45
	v_cvt_pk_bf16_f32 v209, v46, v47
	v_cvt_pk_bf16_f32 v210, v40, v41
	v_cvt_pk_bf16_f32 v211, v42, v43
	v_cvt_pk_bf16_f32 v212, v36, v37
	v_cvt_pk_bf16_f32 v213, v38, v39
	v_cvt_pk_bf16_f32 v214, v32, v33
	v_cvt_pk_bf16_f32 v215, v34, v35
	ds_bpermute_b32 v216, v204, v208
	ds_bpermute_b32 v217, v204, v209
	ds_bpermute_b32 v218, v204, v210
	ds_bpermute_b32 v219, v204, v211
	ds_bpermute_b32 v220, v204, v212
	ds_bpermute_b32 v221, v204, v213
	ds_bpermute_b32 v222, v204, v214
	ds_bpermute_b32 v223, v204, v215
	s_waitcnt lgkmcnt(8)
	global_store_dwordx4 v207, v[196:199], s[64:65]
	global_store_dwordx4 v207, v[200:203], s[64:65] offset:256
	v_add_u32_e32 v207, 0x8000, v207
	v_cvt_pk_bf16_f32 v188, v28, v29
	v_cvt_pk_bf16_f32 v189, v30, v31
	v_cvt_pk_bf16_f32 v190, v24, v25
	v_cvt_pk_bf16_f32 v191, v26, v27
	v_cvt_pk_bf16_f32 v192, v20, v21
	v_cvt_pk_bf16_f32 v193, v22, v23
	v_cvt_pk_bf16_f32 v194, v16, v17
	v_cvt_pk_bf16_f32 v195, v18, v19
	ds_bpermute_b32 v196, v204, v188
	ds_bpermute_b32 v197, v204, v189
	ds_bpermute_b32 v198, v204, v190
	ds_bpermute_b32 v199, v204, v191
	ds_bpermute_b32 v200, v204, v192
	ds_bpermute_b32 v201, v204, v193
	ds_bpermute_b32 v202, v204, v194
	ds_bpermute_b32 v203, v204, v195
	s_waitcnt lgkmcnt(8)
	global_store_dwordx4 v207, v[216:219], s[64:65]
	global_store_dwordx4 v207, v[220:223], s[64:65] offset:256
	v_add_u32_e32 v207, 0x8000, v207
	v_cvt_pk_bf16_f32 v208, v12, v13
	v_cvt_pk_bf16_f32 v209, v14, v15
	v_cvt_pk_bf16_f32 v210, v8, v9
	v_cvt_pk_bf16_f32 v211, v10, v11
	v_cvt_pk_bf16_f32 v212, v4, v5
	v_cvt_pk_bf16_f32 v213, v6, v7
	v_cvt_pk_bf16_f32 v214, v0, v1
	v_cvt_pk_bf16_f32 v215, v2, v3
	ds_bpermute_b32 v216, v204, v208
	ds_bpermute_b32 v217, v204, v209
	ds_bpermute_b32 v218, v204, v210
	ds_bpermute_b32 v219, v204, v211
	ds_bpermute_b32 v220, v204, v212
	ds_bpermute_b32 v221, v204, v213
	ds_bpermute_b32 v222, v204, v214
	ds_bpermute_b32 v223, v204, v215
	s_waitcnt lgkmcnt(8)
	global_store_dwordx4 v207, v[196:199], s[64:65]
	global_store_dwordx4 v207, v[200:203], s[64:65] offset:256
	v_add_u32_e32 v207, 0x8000, v207
	s_waitcnt lgkmcnt(0)
	global_store_dwordx4 v207, v[216:219], s[64:65]
	global_store_dwordx4 v207, v[220:223], s[64:65] offset:256
	s_and_b64 vcc, exec, s[8:9]
	s_mov_b64 s[8:9], -1
	s_cbranch_vccnz .LBB0_386
	s_andn2_b64 vcc, exec, s[22:23]
	s_cbranch_vccnz .LBB0_385
	s_barrier
	s_branch .LBB0_385
